# decode-state write-back (S'=aS+kv) deferred from the mixer phase to the workgroups idle in the last W_up round (hand-written streaming pass)
# baseline (speedup 1.0000x reference)
; #define LAS __attribute__((address_space(3)))
; template <bool WITH_O> __device__ __forceinline__ void gla_sample(LAS unsigned char* lds, int uidx, const float* PRS, const float* GLRP, const float* w2, const float* gb, const float* gn, ...
;     ...
;     const int dv4 = (tid & 63) * 4; const f32x4 v = prs_sum4(PRS, s, 4096 + h * DV + dv4);
;     __syncthreads();
;     f32x4 o = {0.f, 0.f, 0.f, 0.f};
; #pragma unroll
;     for (int kk = 0; kk < 16; ++kk) { const int k = 16 * wid + kk; const f32x4 sn = S[kk] * smA[k] + v * smK[k]; if (!WITH_O || !DEFER_STATE) __builtin_nontemporal_store(sn, (f32x4*)(s_out + sb + (size_t)k * DV)); if (WITH_O) o += sn * smQ[k]; }
;     if (!WITH_O) { __syncthreads(); return; }
;     *(LAS f32x4*)(smO + wid * 256 + dv4) = o;
.LBB0_362:
	s_or_b64 exec, exec, s[52:53]
	s_lshl_b32 s48, s6, 8
	v_or_b32_e32 v64, s48, v121
	v_lshlrev_b32_e32 v168, 2, v64
	v_lshl_add_u64 v[64:65], s[22:23], 0, v[168:169]
	v_lshl_add_u64 v[68:69], v[64:65], 0, v[72:73]
	v_add_co_u32_e32 v64, vcc, 0x4000, v68
	v_mov_b32_e32 v78, s10
	s_nop 0
	v_addc_co_u32_e32 v65, vcc, 0, v69, vcc
	global_load_dwordx4 v[64:67], v[64:65], off
	s_mov_b32 s6, 0x4768000
	s_waitcnt vmcnt(0)
	v_pk_add_f32 v[74:75], v[64:65], 0 op_sel_hi:[1,0]
	v_add_co_u32_e32 v64, vcc, 0x324000, v68
	v_pk_add_f32 v[70:71], v[66:67], 0 op_sel_hi:[1,0]
	s_nop 0
	v_addc_co_u32_e32 v65, vcc, 0, v69, vcc
	global_load_dwordx4 v[64:67], v[64:65], off
	s_waitcnt vmcnt(0)
	v_pk_add_f32 v[74:75], v[74:75], v[64:65]
	v_add_co_u32_e32 v64, vcc, 0x644000, v68
	v_pk_add_f32 v[70:71], v[70:71], v[66:67]
	s_nop 0
	v_addc_co_u32_e32 v65, vcc, 0, v69, vcc
	global_load_dwordx4 v[64:67], v[64:65], off
	s_waitcnt vmcnt(0)
	v_pk_add_f32 v[76:77], v[74:75], v[64:65]
	v_add_co_u32_e32 v64, vcc, 0x964000, v68
	v_pk_add_f32 v[70:71], v[70:71], v[66:67]
	s_nop 0
	v_addc_co_u32_e32 v65, vcc, 0, v69, vcc
	global_load_dwordx4 v[64:67], v[64:65], off
	s_waitcnt lgkmcnt(0)
	s_barrier
	ds_read_b128 v[80:83], v78 offset:512
	s_waitcnt vmcnt(0)
	v_pk_add_f32 v[74:75], v[70:71], v[66:67]
	v_pk_add_f32 v[76:77], v[76:77], v[64:65]
	ds_read_b128 v[84:87], v78
	ds_read_b128 v[68:71], v78 offset:16
	ds_read_b128 v[64:67], v78 offset:32
	s_waitcnt lgkmcnt(3)
	v_pk_mul_f32 v[88:89], v[74:75], v[80:81] op_sel_hi:[1,0]
	v_pk_mul_f32 v[92:93], v[76:77], v[80:81] op_sel_hi:[1,0]
	s_waitcnt lgkmcnt(2)
	v_pk_fma_f32 v[90:91], v[62:63], v[84:85], v[88:89] op_sel_hi:[1,0,1]
	v_pk_fma_f32 v[88:89], v[60:61], v[84:85], v[92:93] op_sel_hi:[1,0,1]
	v_lshl_add_u64 v[60:61], s[28:29], 0, v[114:115]
	ds_read_b128 v[92:95], v78 offset:1024
	v_add_co_u32_e32 v96, vcc, s6, v60
	s_mov_b32 s6, 0x4769000
	s_nop 0
	v_addc_co_u32_e32 v97, vcc, 0, v61, vcc
	v_add_co_u32_e32 v62, vcc, s6, v60
	v_pk_mul_f32 v[98:99], v[74:75], v[80:81] op_sel:[0,1]
	s_nop 0
	v_addc_co_u32_e32 v63, vcc, 0, v61, vcc
	v_pk_mul_f32 v[80:81], v[76:77], v[80:81] op_sel:[0,1]
	v_pk_fma_f32 v[58:59], v[58:59], v[84:85], v[98:99] op_sel:[0,1,0]
	v_pk_fma_f32 v[56:57], v[56:57], v[84:85], v[80:81] op_sel:[0,1,0]
	s_waitcnt lgkmcnt(0)
	v_pk_fma_f32 v[88:89], v[88:89], v[92:93], 0 op_sel_hi:[1,0,0]
	v_pk_mul_f32 v[80:81], v[74:75], v[82:83] op_sel_hi:[1,0]
	v_pk_mul_f32 v[84:85], v[76:77], v[82:83] op_sel_hi:[1,0]
	v_pk_fma_f32 v[90:91], v[90:91], v[92:93], 0 op_sel_hi:[1,0,0]
	v_pk_fma_f32 v[54:55], v[54:55], v[86:87], v[80:81] op_sel_hi:[1,0,1]
	v_pk_fma_f32 v[52:53], v[52:53], v[86:87], v[84:85] op_sel_hi:[1,0,1]
	v_pk_fma_f32 v[56:57], v[56:57], v[92:93], v[88:89] op_sel:[0,1,0]
	v_pk_fma_f32 v[58:59], v[58:59], v[92:93], v[90:91] op_sel:[0,1,0]
	v_mov_b32_e32 v80, v87
	s_mov_b32 s6, 0x476a000
	v_pk_fma_f32 v[52:53], v[52:53], v[94:95], v[56:57] op_sel_hi:[1,0,1]
	v_mov_b32_e32 v56, v83
	v_pk_fma_f32 v[54:55], v[54:55], v[94:95], v[58:59] op_sel_hi:[1,0,1]
	v_pk_mul_f32 v[58:59], v[74:75], v[56:57] op_sel_hi:[1,0]
	v_pk_mul_f32 v[56:57], v[76:77], v[56:57] op_sel_hi:[1,0]
	v_pk_fma_f32 v[50:51], v[50:51], v[80:81], v[58:59] op_sel_hi:[1,0,1]
	v_pk_fma_f32 v[48:49], v[48:49], v[80:81], v[56:57] op_sel_hi:[1,0,1]
	v_mov_b32_e32 v56, v95
	v_pk_fma_f32 v[58:59], v[50:51], v[56:57], v[54:55] op_sel_hi:[1,0,1]
	v_pk_fma_f32 v[56:57], v[48:49], v[56:57], v[52:53] op_sel_hi:[1,0,1]
	ds_read_b128 v[48:51], v78 offset:528
	s_waitcnt lgkmcnt(0)
	v_pk_mul_f32 v[52:53], v[74:75], v[48:49] op_sel_hi:[1,0]
	v_pk_mul_f32 v[54:55], v[76:77], v[48:49] op_sel_hi:[1,0]
	v_pk_fma_f32 v[46:47], v[46:47], v[68:69], v[52:53] op_sel_hi:[1,0,1]
	v_pk_fma_f32 v[44:45], v[44:45], v[68:69], v[54:55] op_sel_hi:[1,0,1]
	ds_read_b128 v[52:55], v78 offset:1040
	s_waitcnt lgkmcnt(0)
	s_nop 0
	v_pk_fma_f32 v[44:45], v[44:45], v[52:53], v[56:57] op_sel_hi:[1,0,1]
	v_pk_mul_f32 v[56:57], v[74:75], v[48:49] op_sel:[0,1]
	v_pk_mul_f32 v[48:49], v[76:77], v[48:49] op_sel:[0,1]
	v_pk_fma_f32 v[46:47], v[46:47], v[52:53], v[58:59] op_sel_hi:[1,0,1]
	v_pk_fma_f32 v[42:43], v[42:43], v[68:69], v[56:57] op_sel:[0,1,0]
	v_pk_fma_f32 v[40:41], v[40:41], v[68:69], v[48:49] op_sel:[0,1,0]
	s_nop 1
	v_pk_fma_f32 v[42:43], v[42:43], v[52:53], v[46:47] op_sel:[0,1,0]
	v_pk_fma_f32 v[40:41], v[40:41], v[52:53], v[44:45] op_sel:[0,1,0]
	v_pk_mul_f32 v[44:45], v[74:75], v[50:51] op_sel_hi:[1,0]
	v_pk_mul_f32 v[46:47], v[76:77], v[50:51] op_sel_hi:[1,0]
	v_pk_fma_f32 v[38:39], v[38:39], v[70:71], v[44:45] op_sel_hi:[1,0,1]
	v_pk_fma_f32 v[36:37], v[36:37], v[70:71], v[46:47] op_sel_hi:[1,0,1]
	v_mov_b32_e32 v44, v71
	s_nop 0
	v_pk_fma_f32 v[36:37], v[36:37], v[54:55], v[40:41] op_sel_hi:[1,0,1]
	v_mov_b32_e32 v40, v51
	v_pk_fma_f32 v[38:39], v[38:39], v[54:55], v[42:43] op_sel_hi:[1,0,1]
	v_pk_mul_f32 v[42:43], v[74:75], v[40:41] op_sel_hi:[1,0]
	v_pk_mul_f32 v[40:41], v[76:77], v[40:41] op_sel_hi:[1,0]
	v_pk_fma_f32 v[34:35], v[34:35], v[44:45], v[42:43] op_sel_hi:[1,0,1]
	v_pk_fma_f32 v[32:33], v[32:33], v[44:45], v[40:41] op_sel_hi:[1,0,1]
	v_mov_b32_e32 v40, v55
	v_pk_fma_f32 v[44:45], v[34:35], v[40:41], v[38:39] op_sel_hi:[1,0,1]
	v_pk_fma_f32 v[46:47], v[32:33], v[40:41], v[36:37] op_sel_hi:[1,0,1]
	ds_read_b128 v[32:35], v78 offset:544
	s_waitcnt lgkmcnt(0)
; #define LAS __attribute__((address_space(3)))
; template <bool WITH_O> __device__ __forceinline__ void gla_sample(LAS unsigned char* lds, int uidx, const float* PRS, const float* GLRP, const float* w2, const float* gb, const float* gn, ...
;     ...
;     for (int kk = 0; kk < 16; ++kk) { const int k = 16 * wid + kk; const f32x4 sn = S[kk] * smA[k] + v * smK[k]; if (!WITH_O || !DEFER_STATE) __builtin_nontemporal_store(sn, (f32x4*)(s_out + sb + (size_t)k * DV)); if (WITH_O) o += sn * smQ[k]; }
;     if (!WITH_O) { __syncthreads(); return; }
;     *(LAS f32x4*)(smO + wid * 256 + dv4) = o;
;     __syncthreads();
;     float oo = 0.f;
;     if (tid < 256) {
; #pragma unroll
;         for (int w = 0; w < 8; ++w) oo += smO[w * 256 + tid];
;         const float ss = wave_sum(oo * oo); if (lane == 0) smR[wid] = ss; }
	v_pk_mul_f32 v[36:37], v[74:75], v[32:33] op_sel_hi:[1,0]
	v_pk_mul_f32 v[40:41], v[76:77], v[32:33] op_sel_hi:[1,0]
	v_pk_fma_f32 v[38:39], v[30:31], v[64:65], v[36:37] op_sel_hi:[1,0,1]
	v_pk_fma_f32 v[36:37], v[28:29], v[64:65], v[40:41] op_sel_hi:[1,0,1]
	ds_read_b128 v[40:43], v78 offset:1056
	v_add_co_u32_e32 v30, vcc, s6, v60
	s_mov_b32 s6, 0x476b000
	s_nop 0
	v_addc_co_u32_e32 v31, vcc, 0, v61, vcc
	v_add_co_u32_e32 v28, vcc, s6, v60
	s_nop 1
	v_addc_co_u32_e32 v29, vcc, 0, v61, vcc
	s_waitcnt lgkmcnt(0)
	s_nop 0
	v_pk_fma_f32 v[38:39], v[38:39], v[40:41], v[44:45] op_sel_hi:[1,0,1]
	v_pk_mul_f32 v[44:45], v[74:75], v[32:33] op_sel:[0,1]
	v_pk_mul_f32 v[32:33], v[76:77], v[32:33] op_sel:[0,1]
	v_pk_fma_f32 v[36:37], v[36:37], v[40:41], v[46:47] op_sel_hi:[1,0,1]
	v_pk_fma_f32 v[26:27], v[26:27], v[64:65], v[44:45] op_sel:[0,1,0]
	v_pk_fma_f32 v[24:25], v[24:25], v[64:65], v[32:33] op_sel:[0,1,0]
	v_pk_mul_f32 v[32:33], v[74:75], v[34:35] op_sel_hi:[1,0]
	s_nop 0
	v_pk_fma_f32 v[24:25], v[24:25], v[40:41], v[36:37] op_sel:[0,1,0]
	v_pk_mul_f32 v[36:37], v[76:77], v[34:35] op_sel_hi:[1,0]
	v_pk_fma_f32 v[22:23], v[22:23], v[66:67], v[32:33] op_sel_hi:[1,0,1]
	v_pk_fma_f32 v[20:21], v[20:21], v[66:67], v[36:37] op_sel_hi:[1,0,1]
	v_pk_fma_f32 v[26:27], v[26:27], v[40:41], v[38:39] op_sel:[0,1,0]
	v_pk_fma_f32 v[24:25], v[20:21], v[42:43], v[24:25] op_sel_hi:[1,0,1]
	v_mov_b32_e32 v32, v67
	v_mov_b32_e32 v20, v35
	v_pk_fma_f32 v[22:23], v[22:23], v[42:43], v[26:27] op_sel_hi:[1,0,1]
	v_pk_mul_f32 v[26:27], v[74:75], v[20:21] op_sel_hi:[1,0]
	v_pk_mul_f32 v[20:21], v[76:77], v[20:21] op_sel_hi:[1,0]
	v_pk_fma_f32 v[18:19], v[18:19], v[32:33], v[26:27] op_sel_hi:[1,0,1]
	v_pk_fma_f32 v[16:17], v[16:17], v[32:33], v[20:21] op_sel_hi:[1,0,1]
	v_mov_b32_e32 v26, v43
	v_pk_fma_f32 v[20:21], v[18:19], v[26:27], v[22:23] op_sel_hi:[1,0,1]
	v_pk_fma_f32 v[22:23], v[16:17], v[26:27], v[24:25] op_sel_hi:[1,0,1]
	ds_read_b128 v[16:19], v78 offset:48
	ds_read_b128 v[24:27], v78 offset:560
	s_waitcnt lgkmcnt(0)
	v_pk_mul_f32 v[30:31], v[74:75], v[24:25] op_sel_hi:[1,0]
	v_pk_mul_f32 v[32:33], v[76:77], v[24:25] op_sel_hi:[1,0]
	v_pk_fma_f32 v[14:15], v[14:15], v[16:17], v[30:31] op_sel_hi:[1,0,1]
	v_pk_fma_f32 v[12:13], v[12:13], v[16:17], v[32:33] op_sel_hi:[1,0,1]
	ds_read_b128 v[30:33], v78 offset:1072
	s_waitcnt lgkmcnt(0)
	s_nop 0
	v_pk_fma_f32 v[14:15], v[14:15], v[30:31], v[20:21] op_sel_hi:[1,0,1]
	v_pk_fma_f32 v[12:13], v[12:13], v[30:31], v[22:23] op_sel_hi:[1,0,1]
	v_pk_mul_f32 v[20:21], v[74:75], v[24:25] op_sel:[0,1]
	v_pk_mul_f32 v[22:23], v[76:77], v[24:25] op_sel:[0,1]
	v_pk_fma_f32 v[10:11], v[10:11], v[16:17], v[20:21] op_sel:[0,1,0]
	v_pk_fma_f32 v[8:9], v[8:9], v[16:17], v[22:23] op_sel:[0,1,0]
	s_nop 1
	v_pk_fma_f32 v[10:11], v[10:11], v[30:31], v[14:15] op_sel:[0,1,0]
	v_pk_fma_f32 v[8:9], v[8:9], v[30:31], v[12:13] op_sel:[0,1,0]
	v_pk_mul_f32 v[12:13], v[74:75], v[26:27] op_sel_hi:[1,0]
	v_pk_mul_f32 v[14:15], v[76:77], v[26:27] op_sel_hi:[1,0]
	v_pk_fma_f32 v[6:7], v[6:7], v[18:19], v[12:13] op_sel_hi:[1,0,1]
	v_pk_fma_f32 v[4:5], v[4:5], v[18:19], v[14:15] op_sel_hi:[1,0,1]
	v_mov_b32_e32 v12, v19
	s_nop 0
	v_pk_fma_f32 v[4:5], v[4:5], v[32:33], v[8:9] op_sel_hi:[1,0,1]
	v_mov_b32_e32 v8, v27
	v_pk_fma_f32 v[6:7], v[6:7], v[32:33], v[10:11] op_sel_hi:[1,0,1]
	v_pk_mul_f32 v[10:11], v[74:75], v[8:9] op_sel_hi:[1,0]
	v_pk_mul_f32 v[8:9], v[76:77], v[8:9] op_sel_hi:[1,0]
	v_pk_fma_f32 v[2:3], v[2:3], v[12:13], v[10:11] op_sel_hi:[1,0,1]
	v_pk_fma_f32 v[0:1], v[0:1], v[12:13], v[8:9] op_sel_hi:[1,0,1]
	v_mov_b32_e32 v8, v33
	s_nop 1
	v_pk_fma_f32 v[2:3], v[2:3], v[8:9], v[6:7] op_sel_hi:[1,0,1]
	v_pk_fma_f32 v[0:1], v[0:1], v[8:9], v[4:5] op_sel_hi:[1,0,1]
	ds_write_b128 v123, v[0:3] offset:1536
	v_mov_b32_e32 v0, 0
	s_waitcnt lgkmcnt(0)
	s_barrier
	s_and_saveexec_b64 s[6:7], s[40:41]
	s_cbranch_execz .LBB0_366
	ds_read2st64_b32 v[0:1], v122 offset0:6 offset1:10
	v_xor_b32_e32 v3, 1, v211
	s_waitcnt lgkmcnt(0)
	v_add_f32_e32 v0, 0, v0
	v_add_f32_e32 v2, v0, v1
	ds_read2st64_b32 v[0:1], v122 offset0:14 offset1:18
	s_waitcnt lgkmcnt(0)
	v_add_f32_e32 v0, v2, v0
	v_add_f32_e32 v2, v0, v1
	ds_read2st64_b32 v[0:1], v122 offset0:22 offset1:26
	s_waitcnt lgkmcnt(0)
	v_add_f32_e32 v0, v2, v0
	v_add_f32_e32 v2, v0, v1
	ds_read2st64_b32 v[0:1], v122 offset0:30 offset1:34
	s_waitcnt lgkmcnt(0)
	v_add_f32_e32 v0, v2, v0
	v_and_b32_e32 v2, 64, v211
	v_add_u32_e32 v2, 64, v2
	v_cmp_lt_i32_e32 vcc, v3, v2
	v_add_f32_e32 v0, v0, v1
	v_mul_f32_e32 v1, v0, v0
	v_cndmask_b32_e32 v3, v211, v3, vcc
	v_lshlrev_b32_e32 v3, 2, v3
	ds_bpermute_b32 v1, v3, v1
	v_xor_b32_e32 v3, 2, v211
	v_cmp_lt_i32_e32 vcc, v3, v2
	s_waitcnt lgkmcnt(0)
	v_fmac_f32_e32 v1, v0, v0
	v_cndmask_b32_e32 v3, v211, v3, vcc
	v_lshlrev_b32_e32 v3, 2, v3
	ds_bpermute_b32 v3, v3, v1
	s_waitcnt lgkmcnt(0)
	v_add_f32_e32 v1, v1, v3
	v_xor_b32_e32 v3, 4, v211
	v_cmp_lt_i32_e32 vcc, v3, v2
	s_nop 1
	v_cndmask_b32_e32 v3, v211, v3, vcc
	v_lshlrev_b32_e32 v3, 2, v3
	ds_bpermute_b32 v3, v3, v1
	s_waitcnt lgkmcnt(0)
	v_add_f32_e32 v1, v1, v3
	v_xor_b32_e32 v3, 8, v211
	v_cmp_lt_i32_e32 vcc, v3, v2
	s_nop 1
	v_cndmask_b32_e32 v3, v211, v3, vcc
	v_lshlrev_b32_e32 v3, 2, v3
	ds_bpermute_b32 v3, v3, v1
	s_waitcnt lgkmcnt(0)
	v_add_f32_e32 v1, v1, v3
	v_xor_b32_e32 v3, 16, v211
	v_cmp_lt_i32_e32 vcc, v3, v2
	s_nop 1
	v_cndmask_b32_e32 v3, v211, v3, vcc
	v_lshlrev_b32_e32 v3, 2, v3
	ds_bpermute_b32 v3, v3, v1
	s_waitcnt lgkmcnt(0)
	v_add_f32_e32 v1, v1, v3
	v_xor_b32_e32 v3, 32, v211
	v_cmp_lt_i32_e32 vcc, v3, v2
	s_nop 1
	v_cndmask_b32_e32 v2, v211, v3, vcc
	v_lshlrev_b32_e32 v2, 2, v2
	ds_bpermute_b32 v2, v2, v1
	s_and_saveexec_b64 s[8:9], s[44:45]
	s_cbranch_execz .LBB0_365
	s_waitcnt lgkmcnt(0)
	v_add_f32_e32 v1, v1, v2
	v_mov_b32_e32 v2, s54
	ds_write_b32 v2, v1 offset:9728

; __device__ __forceinline__ float logsig_f(float z) { return fminf(z, 0.f) - __logf(1.f + __expf(-fabsf(z))); }
; #define state_gla ((const float*)KPTR(3))
; #define gate_w2 ((const float*)KPTR(8))
; #define gate_b ((const float*)KPTR(9))
; template <bool WITH_O> __device__ __forceinline__ void gla_sample(LAS unsigned char* lds, int uidx, const float* PRS, const float* GLRP, const float* w2, const float* gb, const float* gn, ...
;     ...
;     const size_t sb = ((size_t)(s * 4 + h) * DK) * DV + (tid & 63) * 4; f32x4 S[16];
; #pragma unroll
;     for (int kk = 0; kk < 16; ++kk) S[kk] = __builtin_nontemporal_load((const f32x4*)(s_in + sb + (size_t)(16 * wid + kk) * DV));
;     if (tid < DK) { const int col = h * DK + tid; float z = gb[col];
; #pragma unroll
;         for (int rr = 0; rr < RANK; ++rr) { float g = 0.f;
; #pragma unroll
;             for (int sp = 0; sp < NSP1; ++sp) g += GLRP[((size_t)sp * MPAD + row) * RANK + rr];
;             z += g * w2[rr * QKD + col]; }
;         smA[tid] = __expf(logsig_f(z) * (1.f / 16.f)); smK[tid] = prs_sum(PRS, s, 3584 + col); if (WITH_O) smQ[tid] = prs_sum(PRS, s, 3072 + col) * 0.08838834764831845f; }
;     const int dv4 = (tid & 63) * 4; const f32x4 v = prs_sum4(PRS, s, 4096 + h * DV + dv4);
; __global__ void __launch_bounds__(NTHR, 2) fwd_kernel(Args a) {
;     ...
;             PHASE_IDS const int first = (G == 256) ? 172 : 0, nw = G - first;
;             const float* w2 = gate_w2 + (size_t)l * RANK * QKD; const float* gb = gate_b + (size_t)l * QKD;
;             if (DEFER_STATE && bid >= first) for (int u = bid - first; u < 512; u += nw) gla_sample<false>(lds, u, PRS, GLRP, w2, gb, nullptr, state_gla + (size_t)l * NS * NH * DK * DV, out + O_GS + (size_t)l * NS * NH * DK * DV, nullptr, tid, wid, lane);
.LBB0_820:
	s_mov_b64 s[0:1], s[90:91]
	v_mov_b32_e32 v0, v210
	s_lshr_b32 s4, s96, 3
	s_cmpk_eq_i32 s4, 0x100
	s_cselect_b32 s5, 0xac, 0
	s_sub_i32 s1, s4, s5
	s_sub_i32 s0, s33, s5
	s_cmp_lt_i32 s0, 0
	s_cbranch_scc1 .Ldef_done
	s_load_dwordx2 s[28:29], s[90:91], 0x18
	s_load_dwordx2 s[40:41], s[90:91], 0x40
	s_load_dwordx2 s[42:43], s[90:91], 0x48
	s_load_dwordx2 s[30:31], s[90:91], 0x90
	s_load_dwordx2 s[34:35], s[90:91], 0x98
	v_readlane_b32 s26, v244, 32
	v_readfirstlane_b32 s10, v210
	v_lshlrev_b32_e32 v78, 4, v211
	v_add_u32_e32 v79, 0x1000, v78
	v_add_u32_e32 v80, 0x2000, v78
	v_add_u32_e32 v81, 0x3000, v78
	v_lshlrev_b32_e32 v240, 2, v210
	v_lshrrev_b32_e32 v241, 6, v210
	v_lshlrev_b32_e32 v241, 6, v241
	v_lshrrev_b32_e32 v242, 4, v211
	v_mul_u32_u24_e32 v242, 0x84000, v242
	v_and_b32_e32 v105, 15, v211
	v_lshl_add_u32 v242, v105, 2, v242
	v_add_u32_e32 v237, 16, v211
	v_and_b32_e32 v237, 63, v237
	v_lshlrev_b32_e32 v237, 2, v237
	v_add_u32_e32 v238, 32, v211
	v_and_b32_e32 v238, 63, v238
	v_lshlrev_b32_e32 v238, 2, v238
	v_add_u32_e32 v239, 48, v211
	v_and_b32_e32 v239, 63, v239
	v_lshlrev_b32_e32 v239, 2, v239
	s_lshr_b32 s10, s10, 6
	s_mov_b32 s94, 0
	s_waitcnt lgkmcnt(0)
	s_lshl_b32 s4, s26, 26
	s_add_u32 s28, s28, s4
	s_addc_u32 s29, s29, 0
	s_add_u32 s30, s30, s4
	s_addc_u32 s31, s31, 0
	s_add_u32 s30, s30, 0x4768000
	s_addc_u32 s31, s31, 0
	s_lshl_b32 s4, s26, 15
	s_add_u32 s40, s40, s4
	s_addc_u32 s41, s41, 0
	s_lshl_b32 s4, s26, 11
	s_add_u32 s42, s42, s4
	s_addc_u32 s43, s43, 0
	s_add_u32 s38, s34, 0x212c4000
	s_addc_u32 s39, s35, 0
	s_add_u32 s34, s34, 0x1f9c4000
	s_addc_u32 s35, s35, 0
.Ldef_loop:
	s_lshr_b32 s2, s0, 2
	s_and_b32 s3, s0, 3
	s_mul_i32 s4, s2, 0x6400
	s_add_u32 s50, s34, s4
	s_addc_u32 s51, s35, 0
	s_cmp_gt_u32 s10, 1
	s_cbranch_scc1 .Ldef_nogate
	s_lshl_b32 s5, s3, 9
	v_add_u32_e32 v82, s5, v240
	global_load_dword v83, v82, s[42:43]
	s_lshl_b32 s4, s2, 6
	s_add_u32 s4, s4, 0x80000
	s_add_u32 s52, s38, s4
	s_addc_u32 s53, s39, 0
	global_load_dword v84, v242, s[52:53]
	global_load_dword v85, v82, s[40:41]
	global_load_dword v86, v82, s[40:41] offset:2048
	s_add_u32 s52, s40, 0x1000
	s_addc_u32 s53, s41, 0
	global_load_dword v87, v82, s[52:53]
	global_load_dword v88, v82, s[52:53] offset:2048
	s_add_u32 s52, s40, 0x2000
	s_addc_u32 s53, s41, 0
	global_load_dword v89, v82, s[52:53]
	global_load_dword v90, v82, s[52:53] offset:2048
	s_add_u32 s52, s40, 0x3000
	s_addc_u32 s53, s41, 0
	global_load_dword v91, v82, s[52:53]
	global_load_dword v92, v82, s[52:53] offset:2048
	s_add_u32 s52, s40, 0x4000
	s_addc_u32 s53, s41, 0
	global_load_dword v93, v82, s[52:53]
	global_load_dword v94, v82, s[52:53] offset:2048
	s_add_u32 s52, s40, 0x5000
	s_addc_u32 s53, s41, 0
	global_load_dword v95, v82, s[52:53]
	global_load_dword v96, v82, s[52:53] offset:2048
	s_add_u32 s52, s40, 0x6000
	s_addc_u32 s53, s41, 0
	global_load_dword v97, v82, s[52:53]
	global_load_dword v98, v82, s[52:53] offset:2048
	s_add_u32 s52, s40, 0x7000
	s_addc_u32 s53, s41, 0
	global_load_dword v99, v82, s[52:53]
	global_load_dword v100, v82, s[52:53] offset:2048
	s_add_u32 s52, s50, 0x3800
	s_addc_u32 s53, s51, 0
	global_load_dword v101, v82, s[52:53]
	s_add_u32 s52, s50, 0x323800
	s_addc_u32 s53, s51, 0
	global_load_dword v102, v82, s[52:53]
	s_add_u32 s52, s50, 0x643800
	s_addc_u32 s53, s51, 0
	global_load_dword v103, v82, s[52:53]
	s_add_u32 s52, s50, 0x963800
	s_addc_u32 s53, s51, 0
	global_load_dword v104, v82, s[52:53]
.Ldef_nogate:
	s_lshl_b32 s4, s0, 17
	s_lshl_b32 s5, s10, 14
	s_add_u32 s4, s4, s5
	s_add_u32 s44, s28, s4
	s_addc_u32 s45, s29, 0
	s_add_u32 s48, s30, s4
	s_addc_u32 s49, s31, 0
	global_load_dwordx4 v[128:131], v78, s[44:45] nt
	global_load_dwordx4 v[132:135], v78, s[44:45] offset:1024 nt
	global_load_dwordx4 v[136:139], v78, s[44:45] offset:2048 nt
	global_load_dwordx4 v[140:143], v78, s[44:45] offset:3072 nt
	global_load_dwordx4 v[144:147], v79, s[44:45] nt
	global_load_dwordx4 v[148:151], v79, s[44:45] offset:1024 nt
	global_load_dwordx4 v[152:155], v79, s[44:45] offset:2048 nt
	global_load_dwordx4 v[156:159], v79, s[44:45] offset:3072 nt
	global_load_dwordx4 v[160:163], v80, s[44:45] nt
	global_load_dwordx4 v[164:167], v80, s[44:45] offset:1024 nt
	global_load_dwordx4 v[178:181], v80, s[44:45] offset:2048 nt
	global_load_dwordx4 v[182:185], v80, s[44:45] offset:3072 nt
	global_load_dwordx4 v[186:189], v81, s[44:45] nt
	global_load_dwordx4 v[190:193], v81, s[44:45] offset:1024 nt
	global_load_dwordx4 v[194:197], v81, s[44:45] offset:2048 nt
	global_load_dwordx4 v[198:201], v81, s[44:45] offset:3072 nt
	s_lshl_b32 s4, s3, 10
	s_add_u32 s4, s4, 0x4000
	s_add_u32 s52, s50, s4
	s_addc_u32 s53, s51, 0
	global_load_dwordx4 v[202:205], v78, s[52:53]
	s_add_u32 s52, s50, s4
	s_addc_u32 s53, s51, 0
	s_add_u32 s52, s52, 0x320000
	s_addc_u32 s53, s53, 0
	global_load_dwordx4 v[206:209], v78, s[52:53]
	s_add_u32 s52, s50, s4
	s_addc_u32 s53, s51, 0
	s_add_u32 s52, s52, 0x640000
	s_addc_u32 s53, s53, 0
	global_load_dwordx4 v[228:231], v78, s[52:53]
	s_add_u32 s52, s50, s4
	s_addc_u32 s53, s51, 0
	s_add_u32 s52, s52, 0x960000
	s_addc_u32 s53, s53, 0
	global_load_dwordx4 v[232:235], v78, s[52:53]
	s_cmp_gt_u32 s10, 1
	s_cbranch_scc1 .Ldef_nogate2
; __device__ __forceinline__ float logsig_f(float z) { return fminf(z, 0.f) - __logf(1.f + __expf(-fabsf(z))); }
; template <bool WITH_O> __device__ __forceinline__ void gla_sample(LAS unsigned char* lds, int uidx, const float* PRS, const float* GLRP, const float* w2, const float* gb, const float* gn, ...
;     ...
;     if (tid < DK) { const int col = h * DK + tid; float z = gb[col];
; #pragma unroll
;         for (int rr = 0; rr < RANK; ++rr) { float g = 0.f;
; #pragma unroll
;             for (int sp = 0; sp < NSP1; ++sp) g += GLRP[((size_t)sp * MPAD + row) * RANK + rr];
;             z += g * w2[rr * QKD + col]; }
;         smA[tid] = __expf(logsig_f(z) * (1.f / 16.f)); smK[tid] = prs_sum(PRS, s, 3584 + col); if (WITH_O) smQ[tid] = prs_sum(PRS, s, 3072 + col) * 0.08838834764831845f; }
	s_waitcnt vmcnt(20)
	ds_bpermute_b32 v105, v237, v84
	ds_bpermute_b32 v106, v238, v84
	ds_bpermute_b32 v107, v239, v84
	v_add_f32_e32 v236, 0, v84
	s_waitcnt lgkmcnt(0)
	v_add_f32_e32 v236, v236, v105
	v_add_f32_e32 v236, v236, v106
	v_add_f32_e32 v236, v236, v107
	s_nop 1
	v_readlane_b32 s54, v236, 0
	v_readlane_b32 s55, v236, 1
	v_readlane_b32 s56, v236, 2
	v_readlane_b32 s57, v236, 3
	v_readlane_b32 s58, v236, 4
	v_readlane_b32 s59, v236, 5
	v_readlane_b32 s60, v236, 6
	v_readlane_b32 s62, v236, 7
	v_readlane_b32 s64, v236, 8
	v_readlane_b32 s65, v236, 9
	v_readlane_b32 s66, v236, 10
	v_readlane_b32 s74, v236, 11
	v_readlane_b32 s75, v236, 12
	v_readlane_b32 s77, v236, 13
	v_readlane_b32 s86, v236, 14
	v_readlane_b32 s87, v236, 15
	s_nop 1
	v_fma_f32 v83, s54, v85, v83
	v_fma_f32 v83, s55, v86, v83
	v_fma_f32 v83, s56, v87, v83
	v_fma_f32 v83, s57, v88, v83
	v_fma_f32 v83, s58, v89, v83
	v_fma_f32 v83, s59, v90, v83
	v_fma_f32 v83, s60, v91, v83
	v_fma_f32 v83, s62, v92, v83
	v_fma_f32 v83, s64, v93, v83
	v_fma_f32 v83, s65, v94, v83
	v_fma_f32 v83, s66, v95, v83
	v_fma_f32 v83, s74, v96, v83
	v_fma_f32 v83, s75, v97, v83
	v_fma_f32 v83, s77, v98, v83
	v_fma_f32 v83, s86, v99, v83
	v_fma_f32 v83, s87, v100, v83
	v_mul_f32_e64 v105, |v83|, s17
	v_exp_f32_e32 v105, v105
	v_min_f32_e32 v106, 0, v83
	v_add_f32_e32 v105, 1.0, v105
	v_cmp_gt_f32_e32 vcc, s14, v105
	s_nop 1
	v_cndmask_b32_e64 v107, 0, 32, vcc
	v_ldexp_f32 v105, v105, v107
	v_log_f32_e32 v105, v105
	s_nop 0
	v_mul_f32_e32 v107, 0x3f317217, v105
	v_fma_f32 v107, v105, s18, -v107
	v_fmac_f32_e32 v107, 0x3377d1cf, v105
	v_fmac_f32_e32 v107, 0x3f317217, v105
	v_cmp_lt_f32_e64 s[52:53], |v105|, s19
	s_nop 1
	v_cndmask_b32_e64 v105, v105, v107, s[52:53]
	v_cndmask_b32_e32 v107, 0, v218, vcc
	v_sub_f32_e32 v105, v105, v107
	v_sub_f32_e32 v106, v106, v105
	v_mul_f32_e32 v106, 0x3d800000, v106
	v_mul_f32_e32 v106, 0x3fb8aa3b, v106
	v_exp_f32_e32 v106, v106
	v_add_f32_e32 v105, 0, v101
	v_add_f32_e32 v105, v105, v102
	v_add_f32_e32 v105, v105, v103
	v_add_f32_e32 v105, v105, v104
	v_add_u32_e32 v107, s94, v240
	ds_write2st64_b32 v107, v106, v105 offset1:2
; template <bool WITH_O> __device__ __forceinline__ void gla_sample(LAS unsigned char* lds, int uidx, const float* PRS, const float* GLRP, const float* w2, const float* gb, const float* gn, ...
;     ...
;     __syncthreads();
;     f32x4 o = {0.f, 0.f, 0.f, 0.f};
; #pragma unroll
;     for (int kk = 0; kk < 16; ++kk) { const int k = 16 * wid + kk; const f32x4 sn = S[kk] * smA[k] + v * smK[k]; if (!WITH_O || !DEFER_STATE) __builtin_nontemporal_store(sn, (f32x4*)(s_out + sb + (size_t)k * DV)); if (WITH_O) o += sn * smQ[k]; }
;     if (!WITH_O) { __syncthreads(); return; }
.Ldef_nogate2:
	s_waitcnt lgkmcnt(0)
	s_barrier
	v_add_u32_e32 v107, s94, v241
	ds_read_b128 v[84:87], v107
	ds_read_b128 v[88:91], v107 offset:16
	ds_read_b128 v[92:95], v107 offset:32
	ds_read_b128 v[96:99], v107 offset:48
	ds_read_b128 v[100:103], v107 offset:512
	ds_read_b128 v[24:27], v107 offset:528
	ds_read_b128 v[28:31], v107 offset:544
	ds_read_b128 v[16:19], v107 offset:560
	s_xor_b32 s94, s94, 0x400
	s_waitcnt vmcnt(3)
	v_add_f32_e32 v202, 0, v202
	v_add_f32_e32 v203, 0, v203
	v_add_f32_e32 v204, 0, v204
	v_add_f32_e32 v205, 0, v205
	s_waitcnt vmcnt(2)
	v_add_f32_e32 v202, v202, v206
	v_add_f32_e32 v203, v203, v207
	v_add_f32_e32 v204, v204, v208
	v_add_f32_e32 v205, v205, v209
	s_waitcnt vmcnt(1)
	v_add_f32_e32 v202, v202, v228
	v_add_f32_e32 v203, v203, v229
	v_add_f32_e32 v204, v204, v230
	v_add_f32_e32 v205, v205, v231
	s_waitcnt vmcnt(0)
	v_add_f32_e32 v202, v202, v232
	v_add_f32_e32 v203, v203, v233
	v_add_f32_e32 v204, v204, v234
	v_add_f32_e32 v205, v205, v235
	s_waitcnt lgkmcnt(0)
	v_mul_f32_e32 v206, v202, v100
	v_mul_f32_e32 v207, v203, v100
	v_mul_f32_e32 v208, v204, v100
	v_mul_f32_e32 v209, v205, v100
	v_fma_f32 v128, v128, v84, v206
	v_fma_f32 v129, v129, v84, v207
	v_fma_f32 v130, v130, v84, v208
	v_fma_f32 v131, v131, v84, v209
	global_store_dwordx4 v78, v[128:131], s[48:49] nt
	v_mul_f32_e32 v206, v202, v101
	v_mul_f32_e32 v207, v203, v101
	v_mul_f32_e32 v208, v204, v101
	v_mul_f32_e32 v209, v205, v101
	v_fma_f32 v132, v132, v85, v206
	v_fma_f32 v133, v133, v85, v207
	v_fma_f32 v134, v134, v85, v208
	v_fma_f32 v135, v135, v85, v209
	global_store_dwordx4 v78, v[132:135], s[48:49] offset:1024 nt
	v_mul_f32_e32 v206, v202, v102
	v_mul_f32_e32 v207, v203, v102
	v_mul_f32_e32 v208, v204, v102
	v_mul_f32_e32 v209, v205, v102
	v_fma_f32 v136, v136, v86, v206
	v_fma_f32 v137, v137, v86, v207
	v_fma_f32 v138, v138, v86, v208
	v_fma_f32 v139, v139, v86, v209
	global_store_dwordx4 v78, v[136:139], s[48:49] offset:2048 nt
	v_mul_f32_e32 v206, v202, v103
	v_mul_f32_e32 v207, v203, v103
	v_mul_f32_e32 v208, v204, v103
	v_mul_f32_e32 v209, v205, v103
	v_fma_f32 v140, v140, v87, v206
	v_fma_f32 v141, v141, v87, v207
	v_fma_f32 v142, v142, v87, v208
	v_fma_f32 v143, v143, v87, v209
	global_store_dwordx4 v78, v[140:143], s[48:49] offset:3072 nt
	v_mul_f32_e32 v206, v202, v24
	v_mul_f32_e32 v207, v203, v24
	v_mul_f32_e32 v208, v204, v24
	v_mul_f32_e32 v209, v205, v24
	v_fma_f32 v144, v144, v88, v206
	v_fma_f32 v145, v145, v88, v207
	v_fma_f32 v146, v146, v88, v208
	v_fma_f32 v147, v147, v88, v209
	global_store_dwordx4 v79, v[144:147], s[48:49] nt
	v_mul_f32_e32 v206, v202, v25
	v_mul_f32_e32 v207, v203, v25
	v_mul_f32_e32 v208, v204, v25
	v_mul_f32_e32 v209, v205, v25
	v_fma_f32 v148, v148, v89, v206
	v_fma_f32 v149, v149, v89, v207
	v_fma_f32 v150, v150, v89, v208
	v_fma_f32 v151, v151, v89, v209
	global_store_dwordx4 v79, v[148:151], s[48:49] offset:1024 nt
	v_mul_f32_e32 v206, v202, v26
	v_mul_f32_e32 v207, v203, v26
	v_mul_f32_e32 v208, v204, v26
	v_mul_f32_e32 v209, v205, v26
	v_fma_f32 v152, v152, v90, v206
	v_fma_f32 v153, v153, v90, v207
	v_fma_f32 v154, v154, v90, v208
	v_fma_f32 v155, v155, v90, v209
	global_store_dwordx4 v79, v[152:155], s[48:49] offset:2048 nt
	v_mul_f32_e32 v206, v202, v27
	v_mul_f32_e32 v207, v203, v27
	v_mul_f32_e32 v208, v204, v27
	v_mul_f32_e32 v209, v205, v27
	v_fma_f32 v156, v156, v91, v206
	v_fma_f32 v157, v157, v91, v207
	v_fma_f32 v158, v158, v91, v208
	v_fma_f32 v159, v159, v91, v209
	global_store_dwordx4 v79, v[156:159], s[48:49] offset:3072 nt
	v_mul_f32_e32 v206, v202, v28
	v_mul_f32_e32 v207, v203, v28
	v_mul_f32_e32 v208, v204, v28
	v_mul_f32_e32 v209, v205, v28
	v_fma_f32 v160, v160, v92, v206
	v_fma_f32 v161, v161, v92, v207
	v_fma_f32 v162, v162, v92, v208
	v_fma_f32 v163, v163, v92, v209
	global_store_dwordx4 v80, v[160:163], s[48:49] nt
	v_mul_f32_e32 v206, v202, v29
	v_mul_f32_e32 v207, v203, v29
	v_mul_f32_e32 v208, v204, v29
	v_mul_f32_e32 v209, v205, v29
	v_fma_f32 v164, v164, v93, v206
	v_fma_f32 v165, v165, v93, v207
	v_fma_f32 v166, v166, v93, v208
	v_fma_f32 v167, v167, v93, v209
	global_store_dwordx4 v80, v[164:167], s[48:49] offset:1024 nt
	v_mul_f32_e32 v206, v202, v30
	v_mul_f32_e32 v207, v203, v30
	v_mul_f32_e32 v208, v204, v30
	v_mul_f32_e32 v209, v205, v30
	v_fma_f32 v178, v178, v94, v206
	v_fma_f32 v179, v179, v94, v207
	v_fma_f32 v180, v180, v94, v208
	v_fma_f32 v181, v181, v94, v209
	global_store_dwordx4 v80, v[178:181], s[48:49] offset:2048 nt
	v_mul_f32_e32 v206, v202, v31
	v_mul_f32_e32 v207, v203, v31
	v_mul_f32_e32 v208, v204, v31
	v_mul_f32_e32 v209, v205, v31
	v_fma_f32 v182, v182, v95, v206
	v_fma_f32 v183, v183, v95, v207
	v_fma_f32 v184, v184, v95, v208
	v_fma_f32 v185, v185, v95, v209
	global_store_dwordx4 v80, v[182:185], s[48:49] offset:3072 nt
	v_mul_f32_e32 v206, v202, v16
	v_mul_f32_e32 v207, v203, v16
	v_mul_f32_e32 v208, v204, v16
	v_mul_f32_e32 v209, v205, v16
	v_fma_f32 v186, v186, v96, v206
	v_fma_f32 v187, v187, v96, v207
	v_fma_f32 v188, v188, v96, v208
	v_fma_f32 v189, v189, v96, v209
	global_store_dwordx4 v81, v[186:189], s[48:49] nt
	v_mul_f32_e32 v206, v202, v17
	v_mul_f32_e32 v207, v203, v17
	v_mul_f32_e32 v208, v204, v17
	v_mul_f32_e32 v209, v205, v17
	v_fma_f32 v190, v190, v97, v206
	v_fma_f32 v191, v191, v97, v207
	v_fma_f32 v192, v192, v97, v208
	v_fma_f32 v193, v193, v97, v209
	global_store_dwordx4 v81, v[190:193], s[48:49] offset:1024 nt
	v_mul_f32_e32 v206, v202, v18
	v_mul_f32_e32 v207, v203, v18
	v_mul_f32_e32 v208, v204, v18
	v_mul_f32_e32 v209, v205, v18
	v_fma_f32 v194, v194, v98, v206
	v_fma_f32 v195, v195, v98, v207
	v_fma_f32 v196, v196, v98, v208
	v_fma_f32 v197, v197, v98, v209
	global_store_dwordx4 v81, v[194:197], s[48:49] offset:2048 nt
	v_mul_f32_e32 v206, v202, v19
	v_mul_f32_e32 v207, v203, v19
	v_mul_f32_e32 v208, v204, v19
	v_mul_f32_e32 v209, v205, v19
	v_fma_f32 v198, v198, v99, v206
	v_fma_f32 v199, v199, v99, v207
	v_fma_f32 v200, v200, v99, v208
	v_fma_f32 v201, v201, v99, v209
	global_store_dwordx4 v81, v[198:201], s[48:49] offset:3072 nt
	s_add_i32 s0, s0, s1
	s_cmpk_lt_i32 s0, 0x200
	s_cbranch_scc1 .Ldef_loop
.Ldef_done:
	s_waitcnt vmcnt(0)
	s_waitcnt vmcnt(0)
	s_barrier
	s_mov_b64 s[0:1], exec
	v_readlane_b32 s2, v246, 2
	v_readlane_b32 s3, v246, 3
	s_and_b64 s[2:3], s[0:1], s[2:3]
	s_xor_b64 s[0:1], s[2:3], s[0:1]
	s_mov_b64 exec, s[2:3]
	s_cbranch_execz .LBB0_873
	v_readlane_b32 s2, v245, 56
	s_waitcnt vmcnt(0) expcnt(0) lgkmcnt(0)
	s_nop 0
	v_mov_b32_e32 v0, s2
	ds_read_b32 v2, v0
	v_readlane_b32 s2, v245, 57
	s_waitcnt lgkmcnt(0)
	v_cmp_ne_u32_e32 vcc, 0, v2
	v_mov_b32_e32 v0, s2
	ds_read_b32 v0, v0
	s_cbranch_vccnz .LBB0_836
	s_mov_b32 s8, 1
	s_branch .LBB0_824
